# combo28 + dn_prep step 3 QK^T tiles: the sixteen G values of a lane read once per item (four b128) instead of one LDS round trip per (tile, jj)
# baseline (speedup 1.0000x reference)
; #define LAS __attribute__((address_space(3)))
; __device__ __forceinline__ void dn_prep(const Params& p, LAS unsigned char* lds) {
;     ...
;                     const LAS float* cw = cw_s + j * 384 + part * 128 + d0;
; #pragma unroll
;                     for (int e4 = 0; e4 < 4; ++e4) { const f32x4 c4 = *(const LAS f32x4*)(cw + e4 * 4);
;                         y[e4 * 4] += xv[e4 * 4] * c4[0]; y[e4 * 4 + 1] += xv[e4 * 4 + 1] * c4[1]; y[e4 * 4 + 2] += xv[e4 * 4 + 2] * c4[2]; y[e4 * 4 + 3] += xv[e4 * 4 + 3] * c4[3]; }
;                     if (j == 3 && whist) {
; #pragma unroll
;                         for (int e4 = 0; e4 < 4; ++e4) *(float4*)(hist_out + c0 + e4 * 4) = make_float4(xv[e4 * 4], xv[e4 * 4 + 1], xv[e4 * 4 + 2], xv[e4 * 4 + 3]);
;                     }
;                 }
;                 float ss = 0.f;
; #pragma unroll
;                 for (int e = 0; e < 16; ++e) { y[e] = valid ? silu_f(y[e]) : 0.f; ss += y[e] * y[e]; }
;                 ss = sum8(ss);
;                 if (part < 2) { const float r = rsqrtf(ss + 1e-6f) * (part == 0 ? 0.08838834764831845f : 1.0f);
; #pragma unroll
;                     for (int e = 0; e < 16; ++e) y[e] *= r; }
;                 u32x4 w0, w1;
;                 w0.x = cvt_pk_bf16(y[0], y[1]); w0.y = cvt_pk_bf16(y[2], y[3]); w0.z = cvt_pk_bf16(y[4], y[5]); w0.w = cvt_pk_bf16(y[6], y[7]);
;                 w1.x = cvt_pk_bf16(y[8], y[9]); w1.y = cvt_pk_bf16(y[10], y[11]); w1.z = cvt_pk_bf16(y[12], y[13]); w1.w = cvt_pk_bf16(y[14], y[15]);
;                 if (part == 0) {
;                     *(LAS u32x4*)(Qs + t * 136 + d0) = w0; *(LAS u32x4*)(Qs + t * 136 + d0 + 8) = w1;
;                     bf16_t* qp = gQS + t * 128 + 32 * (sub >> 1) + 4 * (sub & 1);
;                     *(u32x2*)(qp) = (u32x2){w0.x, w0.y}; *(u32x2*)(qp + 8) = (u32x2){w0.z, w0.w}; *(u32x2*)(qp + 16) = (u32x2){w1.x, w1.y}; *(u32x2*)(qp + 24) = (u32x2){w1.z, w1.w};
;                 } else if (part == 1) {
;                     *(LAS u32x4*)(Ks + t * 136 + d0) = w0; *(LAS u32x4*)(Ks + t * 136 + d0 + 8) = w1;
; #pragma unroll
;                     for (int e = 0; e < 16; ++e) Kts[(d0 + e) * 72 + (t ^ (8 * sub))] = f2bf(y[e]);
;                 } else {
; #pragma unroll
;                     for (int e = 0; e < 16; ++e) Vts[(d0 + e) * 72 + (t ^ (8 * sub))] = f2bf(y[e]);
;                 }
;             }
;         }
;         lds_barrier();
.LBB0_283:
	s_or_b64 exec, exec, s[0:1]
	s_waitcnt lgkmcnt(14)
	v_fma_f32 v13, v13, v45, 0
	s_waitcnt lgkmcnt(12)
	v_fma_f32 v5, v5, v25, 0
	s_waitcnt lgkmcnt(11)
	v_fmac_f32_e32 v13, v53, v85
	s_waitcnt lgkmcnt(8)
	v_fmac_f32_e32 v5, v33, v65
	s_waitcnt lgkmcnt(7)
	v_fmac_f32_e32 v13, v93, v109
	s_waitcnt lgkmcnt(4)
	v_fmac_f32_e32 v5, v69, v61
	s_waitcnt lgkmcnt(3)
	v_fmac_f32_e32 v13, v117, v129
	s_waitcnt lgkmcnt(0)
	v_fmac_f32_e32 v5, v57, v17
	v_mul_f32_e32 v17, 0xbfb8aa3b, v13
	v_fma_f32 v12, v12, v44, 0
	v_exp_f32_e32 v17, v17
	v_fma_f32 v4, v4, v24, 0
	v_fmac_f32_e32 v12, v52, v84
	v_fmac_f32_e32 v4, v32, v64
	v_fmac_f32_e32 v12, v92, v108
	v_fmac_f32_e32 v4, v68, v60
	v_fmac_f32_e32 v12, v116, v128
	v_fmac_f32_e32 v4, v56, v16
	v_mul_f32_e32 v16, 0xbfb8aa3b, v12
	v_add_f32_e32 v17, 1.0, v17
	v_fma_f32 v14, v14, v46, 0
	v_fma_f32 v15, v15, v47, 0
	v_exp_f32_e32 v16, v16
	v_rcp_f32_e32 v17, v17
	v_fma_f32 v6, v6, v26, 0
	v_fmac_f32_e32 v14, v54, v86
	v_fmac_f32_e32 v15, v55, v87
	v_fmac_f32_e32 v6, v34, v66
	v_fmac_f32_e32 v14, v94, v110
	v_fmac_f32_e32 v15, v95, v111
	v_fmac_f32_e32 v6, v70, v62
	v_fmac_f32_e32 v14, v118, v130
	v_fmac_f32_e32 v15, v119, v131
	v_fmac_f32_e32 v6, v58, v18
	v_add_f32_e32 v16, 1.0, v16
	v_mul_f32_e32 v18, 0xbfb8aa3b, v14
	v_mul_f32_e32 v13, v13, v17
	v_mul_f32_e32 v17, 0xbfb8aa3b, v15
	v_fma_f32 v8, v8, v36, 0
	v_rcp_f32_e32 v16, v16
	v_exp_f32_e32 v18, v18
	v_exp_f32_e32 v17, v17
	v_fmac_f32_e32 v8, v48, v80
	v_fmac_f32_e32 v8, v88, v104
	v_fmac_f32_e32 v8, v112, v124
	v_mul_f32_e32 v12, v12, v16
	v_add_f32_e32 v16, 1.0, v18
	v_mul_f32_e32 v18, 0xbfb8aa3b, v8
	v_add_f32_e32 v17, 1.0, v17
	v_fma_f32 v10, v10, v38, 0
	v_exp_f32_e32 v18, v18
	v_rcp_f32_e32 v17, v17
	v_fmac_f32_e32 v10, v50, v82
	v_fmac_f32_e32 v10, v90, v106
	v_fmac_f32_e32 v10, v114, v126
	v_add_f32_e32 v18, 1.0, v18
	v_mul_f32_e32 v15, v15, v17
	v_mul_f32_e32 v17, 0xbfb8aa3b, v10
	v_fma_f32 v9, v9, v37, 0
	v_fma_f32 v11, v11, v39, 0
	v_rcp_f32_e32 v18, v18
	v_exp_f32_e32 v17, v17
	v_fma_f32 v7, v7, v27, 0
	v_fmac_f32_e32 v9, v49, v81
	v_fmac_f32_e32 v11, v51, v83
	v_fmac_f32_e32 v7, v35, v67
	v_fmac_f32_e32 v9, v89, v105
	v_fmac_f32_e32 v11, v91, v107
	v_fmac_f32_e32 v7, v71, v63
	v_fmac_f32_e32 v9, v113, v125
	v_fmac_f32_e32 v11, v115, v127
	v_fmac_f32_e32 v7, v59, v19
	v_mul_f32_e32 v19, 0xbfb8aa3b, v9
	v_mul_f32_e32 v8, v8, v18
	v_mul_f32_e32 v18, 0xbfb8aa3b, v11
	v_add_f32_e32 v17, 1.0, v17
	v_fma_f32 v0, v0, v28, 0
	v_fma_f32 v1, v1, v29, 0
	v_rcp_f32_e32 v16, v16
	v_exp_f32_e32 v19, v19
	v_exp_f32_e32 v18, v18
	v_rcp_f32_e32 v17, v17
	v_fmac_f32_e32 v0, v40, v72
	v_fmac_f32_e32 v1, v41, v73
	v_fmac_f32_e32 v0, v76, v96
	v_fmac_f32_e32 v1, v77, v97
	v_fmac_f32_e32 v0, v100, v20
	v_fmac_f32_e32 v1, v101, v21
	v_mul_f32_e32 v14, v14, v16
	v_add_f32_e32 v16, 1.0, v19
	v_add_f32_e32 v18, 1.0, v18
	v_mul_f32_e32 v19, 0xbfb8aa3b, v0
	v_mul_f32_e32 v10, v10, v17
	v_mul_f32_e32 v17, 0xbfb8aa3b, v1
	v_fma_f32 v2, v2, v30, 0
	v_fma_f32 v3, v3, v31, 0
	v_rcp_f32_e32 v16, v16
	v_rcp_f32_e32 v18, v18
	v_exp_f32_e32 v19, v19
	v_exp_f32_e32 v17, v17
	v_fmac_f32_e32 v2, v42, v74
	v_fmac_f32_e32 v3, v43, v75
	v_fmac_f32_e32 v2, v78, v98
	v_fmac_f32_e32 v3, v79, v99
	v_fmac_f32_e32 v2, v102, v22
	v_fmac_f32_e32 v3, v103, v23
	v_mul_f32_e32 v9, v9, v16
	v_mul_f32_e32 v11, v11, v18
	v_add_f32_e32 v16, 1.0, v19
	v_mul_f32_e32 v18, 0xbfb8aa3b, v2
	v_add_f32_e32 v17, 1.0, v17
	v_mul_f32_e32 v19, 0xbfb8aa3b, v3
	v_exp_f32_e32 v18, v18
	v_rcp_f32_e32 v16, v16
	v_rcp_f32_e32 v17, v17
	v_exp_f32_e32 v19, v19
	v_add_f32_e32 v18, 1.0, v18
	v_mul_f32_e32 v0, v0, v16
	v_mul_f32_e32 v1, v1, v17
	v_add_f32_e32 v16, 1.0, v19
	v_mul_f32_e32 v17, 0xbfb8aa3b, v4
	v_rcp_f32_e32 v18, v18
	v_rcp_f32_e32 v16, v16
	v_exp_f32_e32 v17, v17
	v_mul_u32_u24_e32 v120, 0x900, v139
	v_mul_f32_e32 v2, v2, v18
	v_mul_f32_e32 v18, 0xbfb8aa3b, v5
	v_mul_f32_e32 v3, v3, v16
	v_add_f32_e32 v16, 1.0, v17
	v_exp_f32_e32 v18, v18
	v_rcp_f32_e32 v16, v16
	v_cvt_pk_bf16_f32 v0, v0, s0
	v_cndmask_b32_e64 v0, 0, v0, s[24:25]
	v_add_f32_e32 v17, 1.0, v18
	v_mul_f32_e32 v18, 0xbfb8aa3b, v6
	v_mul_f32_e32 v4, v4, v16
	v_add_u32_e32 v16, v144, v120
	v_exp_f32_e32 v18, v18
	ds_write_b16 v16, v0 offset:54400
	v_cvt_pk_bf16_f32 v0, v1, s0
	v_mul_f32_e32 v19, 0xbfb8aa3b, v7
	v_cndmask_b32_e64 v0, 0, v0, s[24:25]
	v_exp_f32_e32 v19, v19
	ds_write_b16 v16, v0 offset:54544
	v_cvt_pk_bf16_f32 v0, v2, s0
	v_rcp_f32_e32 v17, v17
	v_cndmask_b32_e64 v0, 0, v0, s[24:25]
	v_add_f32_e32 v18, 1.0, v18
	ds_write_b16 v16, v0 offset:54688
	v_cvt_pk_bf16_f32 v0, v3, s0
	v_rcp_f32_e32 v18, v18
	v_cndmask_b32_e64 v0, 0, v0, s[24:25]
	v_add_f32_e32 v19, 1.0, v19
	v_cvt_pk_bf16_f32 v12, v12, s0
	v_cvt_pk_bf16_f32 v8, v8, s0
	ds_write_b16 v16, v0 offset:54832
	v_cvt_pk_bf16_f32 v0, v4, s0
	v_rcp_f32_e32 v19, v19
	v_mul_f32_e32 v5, v5, v17
	v_cndmask_b32_e64 v12, 0, v12, s[24:25]
	v_cndmask_b32_e64 v8, 0, v8, s[24:25]
	v_cndmask_b32_e64 v0, 0, v0, s[24:25]
	ds_write_b16 v16, v12 offset:53248
	v_cvt_pk_bf16_f32 v12, v13, s0
	ds_write_b16 v16, v8 offset:53824
	v_cvt_pk_bf16_f32 v8, v9, s0
	ds_write_b16 v16, v0 offset:54976
	v_cvt_pk_bf16_f32 v0, v5, s0
	v_mul_f32_e32 v6, v6, v18
	v_cndmask_b32_e64 v12, 0, v12, s[24:25]
	v_cndmask_b32_e64 v8, 0, v8, s[24:25]
	v_cndmask_b32_e64 v0, 0, v0, s[24:25]
	ds_write_b16 v16, v12 offset:53392
	v_cvt_pk_bf16_f32 v12, v14, s0
	ds_write_b16 v16, v8 offset:53968
	v_cvt_pk_bf16_f32 v8, v10, s0
	ds_write_b16 v16, v0 offset:55120
	v_cvt_pk_bf16_f32 v0, v6, s0
	v_mul_f32_e32 v7, v7, v19
	v_cndmask_b32_e64 v12, 0, v12, s[24:25]
	v_cndmask_b32_e64 v8, 0, v8, s[24:25]
	v_cndmask_b32_e64 v0, 0, v0, s[24:25]
	ds_write_b16 v16, v12 offset:53536
	v_cvt_pk_bf16_f32 v12, v15, s0
	ds_write_b16 v16, v8 offset:54112
	v_cvt_pk_bf16_f32 v8, v11, s0
	ds_write_b16 v16, v0 offset:55264
	v_cvt_pk_bf16_f32 v0, v7, s0
	v_cndmask_b32_e64 v12, 0, v12, s[24:25]
	v_cndmask_b32_e64 v8, 0, v8, s[24:25]
	v_cndmask_b32_e64 v0, 0, v0, s[24:25]
	ds_write_b16 v16, v12 offset:53680
	ds_write_b16 v16, v8 offset:54256
	ds_write_b16 v16, v0 offset:55408
	s_waitcnt lgkmcnt(0)
	s_barrier
; #define LAS __attribute__((address_space(3)))
; __device__ __forceinline__ f32x4 mfma16(const bf16x8& a, const bf16x8& b, const f32x4& c) { return __builtin_amdgcn_mfma_f32_16x16x32_bf16(a, b, c, 0, 0, 0); }
; __device__ __forceinline__ void dn_prep(const Params& p, LAS unsigned char* lds) {
;     ...
;             const int sel = wid >> 2, ti = wid & 3;
;             int z3; asm volatile("v_mov_b32 %0, 0" : "=v"(z3));
;             const int fr = ((tid + z3) & 15), fq = ((tid + z3) & 63) >> 4;
; #pragma unroll
;             for (int tj = 0; tj < 4; ++tj) {
;                 if (sel == 0) {
;                     if (tj <= ti) {
;                         f32x4 acc = {0.f, 0.f, 0.f, 0.f};
; #pragma unroll
;                         for (int kk = 0; kk < 4; ++kk) { const bf16x8 a = *(const LAS bf16x8*)(Ks + (16 * ti + fr) * 136 + kk * 32 + 8 * fq), bb = *(const LAS bf16x8*)(Ks + (16 * tj + fr) * 136 + kk * 32 + 8 * fq); acc = mfma16(a, bb, acc); }
;                         const int j = 16 * tj + fr; const float Gj = G_s[j];
; #pragma unroll
;                         for (int jj = 0; jj < 4; ++jj) { const int i = 16 * ti + 4 * fq + jj;
;                             As[i * 68 + j] = (i > j) ? beta_s[i] * acc[jj] * __expf(G_s[i] - Gj) : 0.f; }
;                     }
;                 } else {
;                     f32x4 acc = {0.f, 0.f, 0.f, 0.f};
;                     if (tj <= ti) {
; #pragma unroll
;                         for (int kk = 0; kk < 4; ++kk) { const bf16x8 a = *(const LAS bf16x8*)(Ks + (16 * tj + fr) * 136 + kk * 32 + 8 * fq), bb = *(const LAS bf16x8*)(Qs + (16 * ti + fr) * 136 + kk * 32 + 8 * fq); acc = mfma16(a, bb, acc); }
;                     }
;                     const int i = 16 * ti + fr; const float Gi = G_s[i];
;                     float v[4];
; #pragma unroll
;                     for (int jj = 0; jj < 4; ++jj) { const int j = 16 * tj + 4 * fq + jj; v[jj] = (i >= j) ? acc[jj] * __expf(Gi - G_s[j]) : 0.f; }
	v_mov_b32 v0, 0
	s_add_u32 s28, s39, s26
	v_add_u32_e32 v0, v0, v184
	v_and_b32_e32 v12, 15, v0
	v_bfe_u32 v1, v0, 4, 2
	v_or_b32_e32 v6, v12, v155
	s_addc_u32 s29, s36, s27
	v_lshlrev_b32_e32 v0, 4, v1
	v_lshlrev_b32_e32 v132, 7, v6
	v_add_u32_e32 v11, 0, v0
	v_lshlrev_b32_e32 v7, 2, v1
	v_lshl_add_u64 v[2:3], s[28:29], 0, v[132:133]
	v_mov_b32_e32 v1, v133
	v_mad_u32_u24 v9, v6, s10, v11
	v_lshl_add_u32 v8, v6, 2, s37
	v_lshl_add_u64 v[4:5], v[2:3], 0, v[0:1]
	v_mul_u32_u24_e32 v13, 0x110, v12
	s_and_saveexec_b64 s[0:1], s[4:5]
	s_xor_b64 s[24:25], exec, s[0:1]
	s_cbranch_execz .LBB0_293
	v_add_u32_e32 v10, v11, v13
	ds_read_b128 v[0:3], v10 offset:17408
	ds_read_b128 v[14:17], v9
	v_cmp_ge_u32_e32 vcc, v6, v7
	ds_read_b128 v[176:179], v10 offset:17472
	ds_read_b128 v[180:183], v9 offset:64
	ds_read_b128 v[186:189], v10 offset:17536
	ds_read_b128 v[190:193], v9 offset:128
	ds_read_b128 v[194:197], v10 offset:17600
	ds_read_b128 v[198:201], v9 offset:192
	v_lshl_add_u32 v218, v7, 2, s37
	ds_read_b128 v[202:205], v218
	ds_read_b128 v[206:209], v218 offset:64
	ds_read_b128 v[210:213], v218 offset:128
	ds_read_b128 v[214:217], v218 offset:192
	s_waitcnt lgkmcnt(10)
	v_mfma_f32_16x16x32_bf16 v[0:3], v[0:3], v[14:17], 0
	s_waitcnt lgkmcnt(8)
	v_mfma_f32_16x16x32_bf16 v[0:3], v[176:179], v[180:183], v[0:3]
	s_waitcnt lgkmcnt(6)
	v_mfma_f32_16x16x32_bf16 v[0:3], v[186:189], v[190:193], v[0:3]
	ds_read_b32 v10, v8
	s_waitcnt lgkmcnt(5)
	v_mfma_f32_16x16x32_bf16 v[0:3], v[194:197], v[198:201], v[0:3]
	v_mov_b32_e32 v14, 0
	v_mov_b32_e32 v15, 0
	s_waitcnt lgkmcnt(0)
	s_and_saveexec_b64 s[0:1], vcc
	s_cbranch_execz .LBB0_286
	v_lshl_add_u32 v15, v7, 2, 0
	v_add_u32_e32 v15, 0x1a500, v15
	v_mov_b32_e32 v15, v202
	v_sub_f32_e32 v15, v10, v15
	v_mul_f32_e32 v15, 0x3fb8aa3b, v15
	v_exp_f32_e32 v15, v15
	s_nop 0
	v_mul_f32_e32 v15, v0, v15
.LBB0_286:
	s_or_b64 exec, exec, s[0:1]
	v_cmp_gt_u32_e32 vcc, v6, v7
	s_nop 1
	v_mov_b32_e32 v0, 0
	s_and_saveexec_b64 s[0:1], vcc
	s_cbranch_execz .LBB0_288
	v_lshl_add_u32 v0, v7, 2, s37
	v_mov_b32_e32 v0, v203
	v_sub_f32_e32 v0, v10, v0
	v_mul_f32_e32 v0, 0x3fb8aa3b, v0
	v_exp_f32_e32 v0, v0
	s_nop 0
	v_mul_f32_e32 v0, v1, v0
.LBB0_288:
	s_or_b64 exec, exec, s[0:1]
	v_or_b32_e32 v1, 2, v7
	v_cmp_ge_u32_e32 vcc, v6, v1
	s_and_saveexec_b64 s[0:1], vcc
	s_cbranch_execz .LBB0_290
	v_lshl_add_u32 v1, v1, 2, 0
	v_add_u32_e32 v1, 0x1a500, v1
	v_mov_b32_e32 v1, v204
	v_sub_f32_e32 v1, v10, v1
	v_mul_f32_e32 v1, 0x3fb8aa3b, v1
	v_exp_f32_e32 v1, v1
	s_nop 0
	v_mul_f32_e32 v14, v2, v1
.LBB0_290:
	s_or_b64 exec, exec, s[0:1]
	v_or_b32_e32 v2, 3, v7
	v_cmp_ge_u32_e32 vcc, v6, v2
	v_mov_b32_e32 v1, 0
	s_and_saveexec_b64 s[0:1], vcc
	s_cbranch_execz .LBB0_292
	v_lshl_add_u32 v1, v2, 2, 0
	v_add_u32_e32 v1, 0x1a500, v1
	v_mov_b32_e32 v1, v205
	v_sub_f32_e32 v1, v10, v1
	v_mul_f32_e32 v1, 0x3fb8aa3b, v1
	v_exp_f32_e32 v1, v1
	s_nop 0
	v_mul_f32_e32 v1, v3, v1

; #define LAS __attribute__((address_space(3)))
; __device__ __forceinline__ f32x4 mfma16(const bf16x8& a, const bf16x8& b, const f32x4& c) { return __builtin_amdgcn_mfma_f32_16x16x32_bf16(a, b, c, 0, 0, 0); }
; __device__ __forceinline__ void dn_prep(const Params& p, LAS unsigned char* lds) {
;     ...
;                 } else {
;                     f32x4 acc = {0.f, 0.f, 0.f, 0.f};
;                     if (tj <= ti) {
; #pragma unroll
;                         for (int kk = 0; kk < 4; ++kk) { const bf16x8 a = *(const LAS bf16x8*)(Ks + (16 * tj + fr) * 136 + kk * 32 + 8 * fq), bb = *(const LAS bf16x8*)(Qs + (16 * ti + fr) * 136 + kk * 32 + 8 * fq); acc = mfma16(a, bb, acc); }
;                     }
;                     const int i = 16 * ti + fr; const float Gi = G_s[i];
;                     float v[4];
; #pragma unroll
;                     for (int jj = 0; jj < 4; ++jj) { const int j = 16 * tj + 4 * fq + jj; v[jj] = (i >= j) ? acc[jj] * __expf(Gi - G_s[j]) : 0.f; }
.LBB0_331:
	s_or_b64 exec, exec, s[28:29]
	ds_read_b32 v16, v8
	v_or_b32_e32 v17, 16, v7
	v_cmp_ge_u32_e32 vcc, v6, v17
	s_waitcnt lgkmcnt(0)
	s_and_saveexec_b64 s[0:1], vcc
	s_cbranch_execz .LBB0_333
	v_lshl_add_u32 v15, v17, 2, 0
	v_add_u32_e32 v15, 0x1a500, v15
	v_mov_b32_e32 v15, v206
	v_sub_f32_e32 v15, v16, v15
	v_mul_f32_e32 v15, 0x3fb8aa3b, v15
	v_exp_f32_e32 v15, v15
	s_nop 0
	v_mul_f32_e32 v15, v0, v15
.LBB0_333:
	s_or_b64 exec, exec, s[0:1]
	v_or_b32_e32 v18, 17, v7
	v_cmp_ge_u32_e32 vcc, v6, v18
	v_mov_b32_e32 v0, 0
	v_mov_b32_e32 v17, 0
	s_and_saveexec_b64 s[0:1], vcc
	s_cbranch_execz .LBB0_335
	v_lshl_add_u32 v17, v18, 2, 0
	v_add_u32_e32 v17, 0x1a500, v17
	v_mov_b32_e32 v17, v207
	v_sub_f32_e32 v17, v16, v17
	v_mul_f32_e32 v17, 0x3fb8aa3b, v17
	v_exp_f32_e32 v17, v17
	s_nop 0
	v_mul_f32_e32 v17, v1, v17
.LBB0_335:
	s_or_b64 exec, exec, s[0:1]
	v_or_b32_e32 v1, 18, v7
	v_cmp_ge_u32_e32 vcc, v6, v1
	s_and_saveexec_b64 s[0:1], vcc
	s_cbranch_execz .LBB0_337
	v_lshl_add_u32 v0, v1, 2, 0
	v_add_u32_e32 v0, 0x1a500, v0
	v_mov_b32_e32 v0, v208
	v_sub_f32_e32 v0, v16, v0
	v_mul_f32_e32 v0, 0x3fb8aa3b, v0
	v_exp_f32_e32 v0, v0
	s_nop 0
	v_mul_f32_e32 v0, v2, v0
.LBB0_337:
	s_or_b64 exec, exec, s[0:1]
	v_or_b32_e32 v2, 19, v7
	v_cmp_ge_u32_e32 vcc, v6, v2
	v_mov_b32_e32 v1, 0
	s_and_saveexec_b64 s[0:1], vcc
	s_cbranch_execz .LBB0_339
	v_lshl_add_u32 v1, v2, 2, 0
	v_add_u32_e32 v1, 0x1a500, v1
	v_mov_b32_e32 v1, v209
	v_sub_f32_e32 v1, v16, v1
	v_mul_f32_e32 v1, 0x3fb8aa3b, v1
	v_exp_f32_e32 v1, v1
	s_nop 0
	v_mul_f32_e32 v1, v3, v1

; #define LAS __attribute__((address_space(3)))
; __device__ __forceinline__ f32x4 mfma16(const bf16x8& a, const bf16x8& b, const f32x4& c) { return __builtin_amdgcn_mfma_f32_16x16x32_bf16(a, b, c, 0, 0, 0); }
; __device__ __forceinline__ void dn_prep(const Params& p, LAS unsigned char* lds) {
;     ...
;                 } else {
;                     f32x4 acc = {0.f, 0.f, 0.f, 0.f};
;                     if (tj <= ti) {
; #pragma unroll
;                         for (int kk = 0; kk < 4; ++kk) { const bf16x8 a = *(const LAS bf16x8*)(Ks + (16 * tj + fr) * 136 + kk * 32 + 8 * fq), bb = *(const LAS bf16x8*)(Qs + (16 * ti + fr) * 136 + kk * 32 + 8 * fq); acc = mfma16(a, bb, acc); }
;                     }
;                     const int i = 16 * ti + fr; const float Gi = G_s[i];
;                     float v[4];
; #pragma unroll
;                     for (int jj = 0; jj < 4; ++jj) { const int j = 16 * tj + 4 * fq + jj; v[jj] = (i >= j) ? acc[jj] * __expf(Gi - G_s[j]) : 0.f; }
.LBB0_343:
	s_or_b64 exec, exec, s[28:29]
	s_waitcnt lgkmcnt(0)
	ds_read_b32 v16, v8
	v_or_b32_e32 v17, 32, v7
	v_cmp_ge_u32_e32 vcc, v6, v17
	s_waitcnt lgkmcnt(0)
	s_and_saveexec_b64 s[0:1], vcc
	s_cbranch_execz .LBB0_345
	v_lshl_add_u32 v15, v17, 2, 0
	v_add_u32_e32 v15, 0x1a500, v15
	v_mov_b32_e32 v15, v210
	v_sub_f32_e32 v15, v16, v15
	v_mul_f32_e32 v15, 0x3fb8aa3b, v15
	v_exp_f32_e32 v15, v15
	s_nop 0
	v_mul_f32_e32 v15, v0, v15
.LBB0_345:
	s_or_b64 exec, exec, s[0:1]
	v_or_b32_e32 v18, 33, v7
	v_cmp_ge_u32_e32 vcc, v6, v18
	v_mov_b32_e32 v0, 0
	v_mov_b32_e32 v17, 0
	s_and_saveexec_b64 s[0:1], vcc
	s_cbranch_execz .LBB0_347
	v_lshl_add_u32 v17, v18, 2, 0
	v_add_u32_e32 v17, 0x1a500, v17
	v_mov_b32_e32 v17, v211
	v_sub_f32_e32 v17, v16, v17
	v_mul_f32_e32 v17, 0x3fb8aa3b, v17
	v_exp_f32_e32 v17, v17
	s_nop 0
	v_mul_f32_e32 v17, v1, v17
.LBB0_347:
	s_or_b64 exec, exec, s[0:1]
	v_or_b32_e32 v1, 34, v7
	v_cmp_ge_u32_e32 vcc, v6, v1
	s_and_saveexec_b64 s[0:1], vcc
	s_cbranch_execz .LBB0_349
	v_lshl_add_u32 v0, v1, 2, 0
	v_add_u32_e32 v0, 0x1a500, v0
	v_mov_b32_e32 v0, v212
	v_sub_f32_e32 v0, v16, v0
	v_mul_f32_e32 v0, 0x3fb8aa3b, v0
	v_exp_f32_e32 v0, v0
	s_nop 0
	v_mul_f32_e32 v0, v2, v0
.LBB0_349:
	s_or_b64 exec, exec, s[0:1]
	v_or_b32_e32 v2, 35, v7
	v_cmp_ge_u32_e32 vcc, v6, v2
	v_mov_b32_e32 v1, 0
	s_and_saveexec_b64 s[0:1], vcc
	s_cbranch_execz .LBB0_351
	v_lshl_add_u32 v1, v2, 2, 0
	v_add_u32_e32 v1, 0x1a500, v1
	v_mov_b32_e32 v1, v213
	v_sub_f32_e32 v1, v16, v1
	v_mul_f32_e32 v1, 0x3fb8aa3b, v1
	v_exp_f32_e32 v1, v1
	s_nop 0
	v_mul_f32_e32 v1, v3, v1

; #define LAS __attribute__((address_space(3)))
; __device__ __forceinline__ f32x4 mfma16(const bf16x8& a, const bf16x8& b, const f32x4& c) { return __builtin_amdgcn_mfma_f32_16x16x32_bf16(a, b, c, 0, 0, 0); }
; __device__ __forceinline__ void dn_prep(const Params& p, LAS unsigned char* lds) {
;     ...
;                 } else {
;                     f32x4 acc = {0.f, 0.f, 0.f, 0.f};
;                     if (tj <= ti) {
; #pragma unroll
;                         for (int kk = 0; kk < 4; ++kk) { const bf16x8 a = *(const LAS bf16x8*)(Ks + (16 * tj + fr) * 136 + kk * 32 + 8 * fq), bb = *(const LAS bf16x8*)(Qs + (16 * ti + fr) * 136 + kk * 32 + 8 * fq); acc = mfma16(a, bb, acc); }
;                     }
;                     const int i = 16 * ti + fr; const float Gi = G_s[i];
;                     float v[4];
; #pragma unroll
;                     for (int jj = 0; jj < 4; ++jj) { const int j = 16 * tj + 4 * fq + jj; v[jj] = (i >= j) ? acc[jj] * __expf(Gi - G_s[j]) : 0.f; }
.LBB0_355:
	s_or_b64 exec, exec, s[28:29]
	ds_read_b32 v8, v8
	v_or_b32_e32 v9, 48, v7
	v_cmp_ge_u32_e32 vcc, v6, v9
	s_waitcnt lgkmcnt(0)
	s_and_saveexec_b64 s[0:1], vcc
	s_cbranch_execz .LBB0_357
	v_lshl_add_u32 v9, v9, 2, 0
	v_add_u32_e32 v9, 0x1a500, v9
	v_mov_b32_e32 v9, v214
	v_sub_f32_e32 v9, v8, v9
	v_mul_f32_e32 v9, 0x3fb8aa3b, v9
	v_exp_f32_e32 v9, v9
	s_nop 0
	v_mul_f32_e32 v10, v0, v9
.LBB0_357:
	s_or_b64 exec, exec, s[0:1]
	v_or_b32_e32 v11, 49, v7
	v_cmp_ge_u32_e32 vcc, v6, v11
	v_mov_b32_e32 v0, 0
	v_mov_b32_e32 v9, 0
	s_and_saveexec_b64 s[0:1], vcc
	s_cbranch_execz .LBB0_359
	v_lshl_add_u32 v9, v11, 2, 0
	v_add_u32_e32 v9, 0x1a500, v9
	v_mov_b32_e32 v9, v215
	v_sub_f32_e32 v9, v8, v9
	v_mul_f32_e32 v9, 0x3fb8aa3b, v9
	v_exp_f32_e32 v9, v9
	s_nop 0
	v_mul_f32_e32 v9, v1, v9
.LBB0_359:
	s_or_b64 exec, exec, s[0:1]
	v_or_b32_e32 v1, 50, v7
	v_cmp_ge_u32_e32 vcc, v6, v1
	s_and_saveexec_b64 s[0:1], vcc
	s_cbranch_execz .LBB0_361
	v_lshl_add_u32 v0, v1, 2, 0
	v_add_u32_e32 v0, 0x1a500, v0
	v_mov_b32_e32 v0, v216
	v_sub_f32_e32 v0, v8, v0
	v_mul_f32_e32 v0, 0x3fb8aa3b, v0
	v_exp_f32_e32 v0, v0
	s_nop 0
	v_mul_f32_e32 v0, v2, v0
.LBB0_361:
	s_or_b64 exec, exec, s[0:1]
	v_or_b32_e32 v2, 51, v7
	v_cmp_ge_u32_e32 vcc, v6, v2
	v_mov_b32_e32 v1, 0
	s_and_saveexec_b64 s[0:1], vcc
	s_cbranch_execz .LBB0_363
	v_lshl_add_u32 v1, v2, 2, 0
	v_add_u32_e32 v1, 0x1a500, v1
	v_mov_b32_e32 v1, v217
	v_sub_f32_e32 v1, v8, v1
	v_mul_f32_e32 v1, 0x3fb8aa3b, v1
	v_exp_f32_e32 v1, v1
	s_nop 0
	v_mul_f32_e32 v1, v3, v1
